# K-loop check of the P5 counter moved to the head of K-tiles 14/15 (more slack)
# speedup vs baseline: 1.0107x; 1.0011x over previous
.LBB0_624:
	s_cmpk_lg_i32 s40, 0x700
	s_cbranch_scc1 .Lk6_go
	s_mov_b64 s[100:101], exec
	v_readlane_b32 s98, v246, 2
	v_readlane_b32 s99, v246, 3
	s_and_b64 s[98:99], s[100:101], s[98:99]
	s_mov_b64 exec, s[98:99]
	s_cbranch_execz .Lk6_chk_end
	s_add_u32 s98, s92, 0x57100
	s_addc_u32 s99, s93, 0
	v_mov_b32_e32 v250, 0
	v_mov_b32_e32 v252, 0x400000
